# attention work queue: next item's ticket atomic issued one item ahead (no exposed atomic round trip at item boundaries)
# baseline (speedup 1.0000x reference)
.LBB0_312:
	s_andn2_b64 vcc, exec, s[0:1]
	s_cbranch_vccnz .LBB0_528
	v_readlane_b32 s0, v254, 53
	v_readlane_b32 s1, v254, 54
	v_mov_b32_e32 v2, v206
	v_readlane_b32 s36, v252, 33
	v_cndmask_b32_e64 v0, 0, 1, s[0:1]
	v_lshlrev_b32_e32 v0, 2, v0
	v_lshl_add_u64 v[146:147], s[26:27], 0, v[0:1]
	v_ashrrev_i32_e32 v0, 3, v2
	v_ashrrev_i32_e32 v164, 6, v2
	v_and_b32_e32 v3, 63, v2
	v_and_b32_e32 v167, 0xffffffe0, v0
	v_mov_b32_e32 v0, 0xfffed000
	v_lshl_add_u32 v171, v164, 3, v0
	v_lshlrev_b32_e32 v0, 2, v3
	v_readlane_b32 s37, v252, 34
	v_readlane_b32 s38, v252, 35
	v_readlane_b32 s39, v252, 36
	v_readlane_b32 s40, v252, 37
	v_readlane_b32 s41, v252, 38
	v_readlane_b32 s42, v252, 39
	v_readlane_b32 s43, v252, 40
	v_readlane_b32 s44, v252, 41
	v_readlane_b32 s45, v252, 42
	v_readlane_b32 s46, v252, 43
	v_readlane_b32 s47, v252, 44
	v_readlane_b32 s48, v252, 45
	v_readlane_b32 s49, v252, 46
	v_readlane_b32 s50, v252, 47
	v_readlane_b32 s51, v252, 48
	v_lshlrev_b32_e32 v4, 11, v164
	v_lshl_add_u64 v[148:149], s[38:39], 0, v[0:1]
	v_readlane_b32 s36, v253, 33
	v_cmp_eq_u32_e64 s[72:73], 0, v2
	s_and_b64 s[0:1], s[0:1], exec
	v_lshlrev_b32_e32 v168, 5, v164
	v_ashrrev_i32_e32 v169, 7, v2
	v_or_b32_e32 v2, v4, v0
	v_lshlrev_b32_e32 v0, 4, v3
	v_readlane_b32 s46, v253, 43
	v_readlane_b32 s47, v253, 44
	v_add_u32_e32 v165, 0x18000, v4
	v_and_b32_e32 v166, 3, v164
	s_cselect_b32 s3, 8, 0
	v_and_b32_e32 v170, 32, v168
	v_cmp_eq_u32_e64 s[6:7], 0, v3
	v_or_b32_e32 v172, 0xffffffc0, v3
	v_add_u32_e32 v173, 0x18000, v2
	v_lshlrev_b16_e32 v174, 3, v164
	v_lshl_add_u64 v[150:151], s[46:47], 0, v[0:1]
	v_readlane_b32 s37, v253, 34
	v_readlane_b32 s38, v253, 35
	v_readlane_b32 s39, v253, 36
	v_readlane_b32 s40, v253, 37
	v_readlane_b32 s41, v253, 38
	v_readlane_b32 s42, v253, 39
	v_readlane_b32 s43, v253, 40
	v_readlane_b32 s44, v253, 41
	v_readlane_b32 s45, v253, 42
	v_readlane_b32 s48, v253, 45
	v_readlane_b32 s49, v253, 46
	v_readlane_b32 s50, v253, 47
	v_readlane_b32 s51, v253, 48
	s_and_saveexec_b64 s[0:1], s[72:73]
	v_mov_b32_e32 v250, 1
	global_atomic_add v251, v[146:147], v250, off sc0
	s_or_b64 exec, exec, s[0:1]
	s_branch .LBB0_316

.LBB0_316:
	s_barrier
	s_and_saveexec_b64 s[0:1], s[72:73]
	s_cbranch_execz .LBB0_320
	s_waitcnt vmcnt(0)
	ds_write_b32 v230, v251
	v_mov_b32_e32 v250, 1
	global_atomic_add v251, v[146:147], v250, off sc0
